# NA item prologue: rel-pos bias loads issued behind the Q loads (in flight with K/V tile 0) instead of two serial load+wait round trips
# speedup vs baseline: 1.0082x; 1.0000x over previous
.LBB0_333:
	v_lshl_add_u32 v0, s34, 9, v115
	s_waitcnt lgkmcnt(0)
	v_mov_b32_e32 v12, v163
	v_ashrrev_i32_e32 v0, 9, v0
	v_bfe_u32 v5, v12, 7, 1
	s_movk_i32 s2, 0x1100
	v_or_b32_e32 v8, v5, v127
	v_mad_i32_i24 v139, v0, s2, v188
	v_lshrrev_b32_e32 v2, 1, v12
	v_and_b32_e32 v138, 15, v12
	v_bfe_u32 v7, v12, 4, 2
	v_mul_i32_i24_e32 v4, 0x1100, v0
	v_lshl_add_u32 v0, v8, 6, v139
	v_and_b32_e32 v6, 32, v2
	v_or3_b32 v122, v0, v6, v138
	v_lshlrev_b32_e32 v0, 4, v7
	v_lshl_add_u64 v[2:3], v[116:117], 0, v[0:1]
	s_movk_i32 s4, 0x1800
	v_or_b32_e32 v120, 16, v122
	v_bfe_u32 v141, v12, 3, 5
	v_mad_i64_i32 v[10:11], s[2:3], v122, s4, v[2:3]
	v_mad_i64_i32 v[2:3], s[2:3], v120, s4, v[2:3]
	v_add_u32_e32 v18, v139, v129
	v_or_b32_e32 v143, 32, v141
	v_and_b32_e32 v28, 0xff, v12
	global_load_dwordx4 v[38:41], v[10:11], off
	global_load_dwordx4 v[34:37], v[10:11], off offset:64
	global_load_dwordx4 v[46:49], v[2:3], off
	global_load_dwordx4 v[42:45], v[2:3], off offset:64
	v_readlane_b32 s6, v252, 60
	v_readlane_b32 s7, v252, 61
	v_add_lshl_u32 v50, v130, v28, 2
	v_mov_b32_e32 v51, 0
	v_cmp_ge_u32_e32 vcc, s12, v28
	v_lshl_add_u64 v[50:51], s[6:7], 0, v[50:51]
	global_load_dword v52, v[50:51], off
	s_and_saveexec_b64 s[6:7], vcc
	global_load_dword v53, v[50:51], off offset:1024
	s_mov_b64 exec, s[6:7]
	v_or_b32_e32 v0, v141, v18
	v_mov_b64_e32 v[2:3], s[26:27]
	v_lshlrev_b32_e32 v12, 3, v12
	v_or_b32_e32 v18, v143, v18
	v_mad_i64_i32 v[10:11], s[2:3], v0, s4, v[2:3]
	v_lshlrev_b32_e32 v0, 1, v114
	v_and_b32_e32 v124, 56, v12
	v_mad_i64_i32 v[2:3], s[2:3], v18, s4, v[2:3]
	v_lshl_add_u64 v[10:11], v[10:11], 0, v[0:1]
	v_lshlrev_b32_e32 v26, 1, v124
	v_mov_b32_e32 v27, v1
	v_lshl_add_u64 v[2:3], v[2:3], 0, v[0:1]
	v_lshl_add_u64 v[14:15], v[10:11], 0, v[26:27]
	s_movk_i32 s5, 0x1000
	v_lshl_add_u64 v[2:3], v[2:3], 0, v[26:27]
	global_load_dwordx4 v[10:13], v[14:15], off offset:2048
	global_load_dwordx4 v[18:21], v[2:3], off offset:2048
	v_add_co_u32_e32 v14, vcc, s5, v14
	v_readlane_b32 s2, v252, 60
	s_nop 0
	v_addc_co_u32_e32 v15, vcc, 0, v15, vcc
	global_load_dwordx4 v[14:17], v[14:15], off
	v_add_co_u32_e32 v2, vcc, s5, v2
	v_readlane_b32 s3, v252, 61
	s_nop 0
	v_addc_co_u32_e32 v3, vcc, 0, v3, vcc
	global_load_dwordx4 v[22:25], v[2:3], off
	v_mul_u32_u24_e32 v2, 0x48, v141
	v_lshlrev_b32_e32 v2, 1, v2
	v_add3_u32 v2, v222, v2, v26
	v_mov_b32_e32 v3, v1
	v_lshlrev_b32_e32 v9, 3, v7
	v_ashrrev_i32_e32 v123, 31, v122
	v_ashrrev_i32_e32 v121, 31, v120
	s_mov_b64 s[4:5], 0
	s_waitcnt vmcnt(3)
	ds_write_b128 v2, v[10:13]
	s_waitcnt vmcnt(1)
	ds_write_b128 v2, v[14:17] offset:18432
	ds_write_b128 v2, v[18:21] offset:4608
	s_waitcnt vmcnt(0)
	ds_write_b128 v2, v[22:25] offset:23040
	v_lshlrev_b32_e32 v10, 2, v28
	v_add_u32_e32 v11, v131, v10
	v_mul_f32_e32 v52, 0x3fb8aa3b, v52
	v_cmp_ge_u32_e32 vcc, s12, v28
	ds_write_b32 v11, v52
	s_and_saveexec_b64 s[4:5], vcc
	v_mul_f32_e32 v53, 0x3fb8aa3b, v53
	ds_write_b32 v11, v53 offset:1024
	s_or_b64 exec, exec, s[4:5]
	v_lshlrev_b32_e32 v134, 2, v7
	v_lshrrev_b32_e32 v7, 2, v138
	v_or_b32_e32 v3, v6, v138
	v_or_b32_e32 v135, v134, v7
	v_and_b32_e32 v7, 12, v10
	v_lshl_add_u32 v136, v7, 1, v222
	v_sub_u32_e64 v7, v3, 8 clamp
	v_sub_u32_e32 v7, v134, v7
	v_sub_u32_e64 v2, v8, 4 clamp
	v_add_u32_e32 v8, 1, v7
	v_cmp_gt_u32_e64 s[42:43], 16, v8
	v_add_u32_e32 v8, 2, v7
	v_cmp_gt_u32_e64 s[44:45], 16, v8
	v_add_u32_e32 v8, 3, v7
	v_cmp_gt_u32_e64 s[46:47], 16, v8
	v_add_u32_e32 v8, 17, v7
	v_cmp_gt_u32_e64 s[50:51], 16, v8
	v_add_u32_e32 v8, 18, v7
	v_cmp_gt_u32_e64 s[52:53], 16, v8
	v_add_u32_e32 v8, 19, v7
	v_cmp_gt_u32_e64 s[54:55], 16, v8
	v_and_b32_e32 v8, -16, v7
	s_movk_i32 s3, 0xffe0
	s_movk_i32 s6, 0xffd0
	v_cmp_eq_u32_e64 s[56:57], s3, v8
	v_cmp_eq_u32_e64 s[64:65], s6, v8
	v_add_u32_e32 v8, 49, v7
	v_min_u32_e32 v3, 40, v3
	v_cmp_gt_u32_e64 s[66:67], 16, v8
	v_add_u32_e32 v8, 50, v7
	v_sub_u32_e32 v3, v134, v3
	v_cmp_gt_u32_e64 s[68:69], 16, v8
	v_add_u32_e32 v8, -7, v3
	v_cmp_gt_u32_e64 s[74:75], 16, v8
	v_add_u32_e32 v8, -6, v3
	v_lshl_add_u32 v145, v9, 1, v222
	v_add_u32_e32 v9, 33, v7
	v_cmp_gt_u32_e64 s[76:77], 16, v8
	v_add_u32_e32 v8, -5, v3
	s_movk_i32 s2, 0xffef
	v_cmp_gt_u32_e64 s[58:59], 16, v9
	v_add_u32_e32 v9, 34, v7
	v_cmp_gt_u32_e64 s[78:79], 16, v8
	v_add_u32_e32 v8, 9, v3
	v_cmp_gt_u32_e64 s[40:41], 16, v7
	v_cmp_lt_u32_e64 s[48:49], s2, v7
	v_cmp_gt_u32_e64 s[60:61], 16, v9
	v_add_u32_e32 v9, 35, v7
	v_add_u32_e32 v7, 51, v7
	v_cmp_gt_u32_e64 s[82:83], 16, v8
	v_add_u32_e32 v8, 10, v3
	v_cmp_gt_u32_e64 s[70:71], 16, v7
	v_add_u32_e32 v7, -8, v3
	v_cmp_gt_u32_e64 s[84:85], 16, v8
	v_add_u32_e32 v8, 11, v3
	v_cmp_gt_u32_e64 s[72:73], 16, v7
	v_cmp_lt_u32_e64 s[80:81], s2, v7
	v_cmp_gt_u32_e64 s[86:87], 16, v8
	v_and_b32_e32 v7, -16, v7
	v_add_u32_e32 v8, 25, v3
	v_cmp_eq_u32_e64 s[88:89], s3, v7
	v_cmp_gt_u32_e64 s[90:91], 16, v8
	v_add_u32_e32 v8, 26, v3
	v_cmp_eq_u32_e64 s[94:95], s6, v7
	v_add_u32_e32 v7, 41, v3
	v_cmp_gt_u32_e64 s[92:93], 16, v8
	v_add_u32_e32 v8, 27, v3
	v_cmp_gt_u32_e64 s[6:7], 16, v7
	v_add_u32_e32 v7, 42, v3
	v_add_u32_e32 v3, 43, v3
	v_cmp_gt_u32_e64 s[96:97], 16, v3
	v_sub_u32_e32 v3, v132, v5
	v_sub_u32_e32 v5, v134, v138
	v_sub_u32_e32 v5, v5, v6
	v_min_u32_e32 v2, 56, v2
	v_mul_i32_i24_e32 v3, 0x7c, v3
	v_lshlrev_b32_e32 v5, 2, v5
	v_mov_b32_e32 v18, v1
	v_mov_b32_e32 v19, v1
	v_mov_b32_e32 v20, v1
	v_mov_b32_e32 v21, v1
	v_cmp_gt_u32_e64 s[62:63], 16, v9
	v_cmp_gt_u32_e64 s[4:5], 16, v8
	v_cmp_gt_u32_e64 s[8:9], 16, v7
	v_add3_u32 v147, v3, v5, v126
	v_sub_u32_e32 v148, v128, v2
	v_add_u32_e32 v149, 0xfffffe00, v4
	v_mov_b64_e32 v[32:33], v[20:21]
	v_mov_b64_e32 v[24:25], v[20:21]
	v_mov_b64_e32 v[28:29], v[20:21]
	v_mov_b64_e32 v[10:11], v[18:19]
	v_mov_b64_e32 v[14:15], v[18:19]
	v_mov_b64_e32 v[2:3], v[18:19]
	v_mov_b64_e32 v[6:7], v[18:19]
	v_lshl_add_u32 v146, v124, 1, v222
	s_mov_b32 s14, 0
	v_mov_b32_e32 v144, 0xf149f2ca
	v_mov_b32_e32 v140, 0
	v_mov_b64_e32 v[30:31], v[18:19]
	v_mov_b64_e32 v[22:23], v[18:19]
	v_mov_b64_e32 v[26:27], v[18:19]
	v_mov_b64_e32 v[12:13], v[20:21]
	v_mov_b64_e32 v[16:17], v[20:21]
	v_mov_b64_e32 v[4:5], v[20:21]
	v_mov_b64_e32 v[8:9], v[20:21]
	v_mov_b32_e32 v137, 0
	v_mov_b32_e32 v142, 0xf149f2ca
	s_mov_b32 s24, 0
	s_waitcnt lgkmcnt(0)
	s_barrier
	s_branch .LBB0_338
